# UP epilogue stores sc1 nt (write-through + streaming) instead of sc1
# speedup vs baseline: 1.0016x; 1.0016x over previous
.LBB0_136:
	s_lshl_b32 s0, s98, 8
	v_mov_b32_e32 v1, v192
	v_mov_b32_e32 v2, v169
	s_add_i32 s0, s0, s82
	s_and_b64 vcc, exec, s[36:37]
	v_add_u32_e32 v182, s0, v1
	s_lshl_b32 s0, s97, 8
	s_or_b32 s0, s0, s83
	v_lshl_add_u32 v2, v2, 3, s0
	v_ashrrev_i32_e32 v3, 31, v2
	v_lshlrev_b64 v[2:3], 1, v[2:3]
	v_ashrrev_i32_e32 v183, 31, v182
	v_lshl_add_u64 v[184:185], s[10:11], 0, v[2:3]
	v_lshlrev_b64 v[132:133], 12, v[182:183]
	v_lshl_add_u64 v[132:133], v[184:185], 0, v[132:133]
	global_load_dwordx4 v[196:199], v[132:133], off
	global_load_dwordx4 v[208:211], v[132:133], off offset:256
	v_add_u32_e32 v190, 16, v182
	v_ashrrev_i32_e32 v191, 31, v190
	v_lshlrev_b64 v[132:133], 12, v[190:191]
	v_lshl_add_u64 v[132:133], v[184:185], 0, v[132:133]
	global_load_dwordx4 v[152:155], v[132:133], off
	global_load_dwordx4 v[148:151], v[132:133], off offset:256
	v_add_u32_e32 v188, 32, v182
	v_ashrrev_i32_e32 v189, 31, v188
	v_lshlrev_b64 v[132:133], 12, v[188:189]
	v_lshl_add_u64 v[132:133], v[184:185], 0, v[132:133]
	global_load_dwordx4 v[144:147], v[132:133], off
	global_load_dwordx4 v[140:143], v[132:133], off offset:256
	v_add_u32_e32 v186, 48, v182
	v_ashrrev_i32_e32 v187, 31, v186
	v_lshlrev_b64 v[132:133], 12, v[186:187]
	v_lshl_add_u64 v[132:133], v[184:185], 0, v[132:133]
	global_load_dwordx4 v[136:139], v[132:133], off
	s_nop 0
	global_load_dwordx4 v[132:135], v[132:133], off offset:256
	v_lshlrev_b32_e32 v250, 12, v182
	v_mov_b32_e32 v251, v0
	v_lshl_add_u64 v[250:251], v[184:185], 0, v[250:251]
	s_mov_b64 s[48:49], 0x80000
	v_lshl_add_u64 v[250:251], v[250:251], 0, s[48:49]
	global_load_dwordx4 v[218:221], v[250:251], off
	global_load_dwordx4 v[222:225], v[250:251], off offset:256
	s_mov_b64 s[48:49], 0x10000
	v_lshl_add_u64 v[250:251], v[250:251], 0, s[48:49]
	global_load_dwordx4 v[226:229], v[250:251], off
	global_load_dwordx4 v[230:233], v[250:251], off offset:256
	v_lshl_add_u64 v[250:251], v[250:251], 0, s[48:49]
	global_load_dwordx4 v[234:237], v[250:251], off
	global_load_dwordx4 v[238:241], v[250:251], off offset:256
	v_lshl_add_u64 v[250:251], v[250:251], 0, s[48:49]
	global_load_dwordx4 v[242:245], v[250:251], off
	global_load_dwordx4 v[246:249], v[250:251], off offset:256
	v_lshlrev_b64 v[212:213], 11, v[182:183]
	s_mov_b64 s[0:1], -1
	s_waitcnt vmcnt(8)
	v_lshlrev_b32_e32 v214, 16, v196
	v_and_b32_e32 v215, 0xffff0000, v196
	v_lshlrev_b32_e32 v196, 16, v197
	v_and_b32_e32 v197, 0xffff0000, v197
	v_lshlrev_b32_e32 v216, 16, v198
	v_and_b32_e32 v217, 0xffff0000, v198
	v_lshlrev_b32_e32 v198, 16, v199
	v_and_b32_e32 v199, 0xffff0000, v199
	v_pk_mul_f32 v[126:127], v[126:127], v[196:197]
	v_pk_mul_f32 v[124:125], v[124:125], v[214:215]
	v_pk_mul_f32 v[128:129], v[128:129], v[216:217]
	v_pk_mul_f32 v[130:131], v[130:131], v[198:199]
	v_cvt_pk_bf16_f32 v124, v124, v125
	v_cvt_pk_bf16_f32 v125, v126, v127
	v_cvt_pk_bf16_f32 v126, v128, v129
	v_lshl_add_u64 v[128:129], s[6:7], 0, v[212:213]
	v_cvt_pk_bf16_f32 v127, v130, v131
	v_lshl_add_u64 v[128:129], v[128:129], 0, v[2:3]
	global_store_dwordx4 v[128:129], v[124:127], off sc1 nt
	v_lshlrev_b32_e32 v130, 16, v210
	v_and_b32_e32 v131, 0xffff0000, v210
	v_lshlrev_b32_e32 v124, 16, v208
	v_and_b32_e32 v125, 0xffff0000, v208
	v_lshlrev_b32_e32 v126, 16, v209
	v_and_b32_e32 v127, 0xffff0000, v209
	v_lshlrev_b32_e32 v196, 16, v211
	v_and_b32_e32 v197, 0xffff0000, v211
	v_pk_mul_f32 v[118:119], v[118:119], v[126:127]
	v_pk_mul_f32 v[116:117], v[116:117], v[124:125]
	v_pk_mul_f32 v[122:123], v[122:123], v[196:197]
	v_pk_mul_f32 v[120:121], v[120:121], v[130:131]
	v_cvt_pk_bf16_f32 v116, v116, v117
	v_cvt_pk_bf16_f32 v117, v118, v119
	v_cvt_pk_bf16_f32 v118, v120, v121
	v_cvt_pk_bf16_f32 v119, v122, v123
	global_store_dwordx4 v[128:129], v[116:119], off offset:256 sc1 nt
	v_lshlrev_b32_e32 v120, 16, v153
	v_and_b32_e32 v121, 0xffff0000, v153
	v_lshlrev_b32_e32 v118, 16, v152
	v_and_b32_e32 v119, 0xffff0000, v152
	v_lshlrev_b32_e32 v122, 16, v154
	v_and_b32_e32 v123, 0xffff0000, v154
	v_lshlrev_b64 v[116:117], 11, v[190:191]
	v_lshlrev_b32_e32 v124, 16, v155
	v_and_b32_e32 v125, 0xffff0000, v155
	v_pk_mul_f32 v[110:111], v[110:111], v[120:121]
	v_pk_mul_f32 v[108:109], v[108:109], v[118:119]
	v_pk_mul_f32 v[112:113], v[112:113], v[122:123]
	v_pk_mul_f32 v[114:115], v[114:115], v[124:125]
	v_cvt_pk_bf16_f32 v108, v108, v109
	v_cvt_pk_bf16_f32 v109, v110, v111
	v_cvt_pk_bf16_f32 v110, v112, v113
	v_lshl_add_u64 v[112:113], s[6:7], 0, v[116:117]
	v_cvt_pk_bf16_f32 v111, v114, v115
	v_lshl_add_u64 v[112:113], v[112:113], 0, v[2:3]
	global_store_dwordx4 v[112:113], v[108:111], off sc1 nt
	v_lshlrev_b32_e32 v114, 16, v150
	v_and_b32_e32 v115, 0xffff0000, v150
	v_lshlrev_b32_e32 v108, 16, v148
	v_and_b32_e32 v109, 0xffff0000, v148
	v_lshlrev_b32_e32 v110, 16, v149
	v_and_b32_e32 v111, 0xffff0000, v149
	v_lshlrev_b32_e32 v116, 16, v151
	v_and_b32_e32 v117, 0xffff0000, v151
	v_pk_mul_f32 v[106:107], v[106:107], v[110:111]
	v_pk_mul_f32 v[104:105], v[104:105], v[108:109]
	v_pk_mul_f32 v[108:109], v[102:103], v[116:117]
	v_pk_mul_f32 v[102:103], v[100:101], v[114:115]
	v_cvt_pk_bf16_f32 v100, v104, v105
	v_cvt_pk_bf16_f32 v101, v106, v107
	v_cvt_pk_bf16_f32 v102, v102, v103
	v_cvt_pk_bf16_f32 v103, v108, v109
	global_store_dwordx4 v[112:113], v[100:103], off offset:256 sc1 nt
	v_lshlrev_b32_e32 v104, 16, v145
	v_and_b32_e32 v105, 0xffff0000, v145
	v_lshlrev_b32_e32 v102, 16, v144
	v_and_b32_e32 v103, 0xffff0000, v144
	v_lshlrev_b64 v[100:101], 11, v[188:189]
	v_lshlrev_b32_e32 v106, 16, v146
	v_and_b32_e32 v107, 0xffff0000, v146
	v_lshlrev_b32_e32 v108, 16, v147
	v_and_b32_e32 v109, 0xffff0000, v147
	v_pk_mul_f32 v[96:97], v[96:97], v[102:103]
	v_pk_mul_f32 v[98:99], v[98:99], v[104:105]
	v_pk_mul_f32 v[102:103], v[94:95], v[108:109]
	v_pk_mul_f32 v[94:95], v[92:93], v[106:107]
	v_cvt_pk_bf16_f32 v92, v96, v97
	v_lshl_add_u64 v[96:97], s[6:7], 0, v[100:101]
	v_cvt_pk_bf16_f32 v93, v98, v99
	v_cvt_pk_bf16_f32 v94, v94, v95
	v_cvt_pk_bf16_f32 v95, v102, v103
	v_lshl_add_u64 v[96:97], v[96:97], 0, v[2:3]
	global_store_dwordx4 v[96:97], v[92:95], off sc1 nt
	v_lshlrev_b32_e32 v98, 16, v142
	v_and_b32_e32 v99, 0xffff0000, v142
	v_lshlrev_b32_e32 v92, 16, v140
	v_and_b32_e32 v93, 0xffff0000, v140
	v_lshlrev_b32_e32 v94, 16, v141
	v_and_b32_e32 v95, 0xffff0000, v141
	v_lshlrev_b32_e32 v100, 16, v143
	v_and_b32_e32 v101, 0xffff0000, v143
	v_pk_mul_f32 v[90:91], v[90:91], v[94:95]
	v_pk_mul_f32 v[88:89], v[88:89], v[92:93]
	v_pk_mul_f32 v[92:93], v[86:87], v[100:101]
	v_pk_mul_f32 v[86:87], v[84:85], v[98:99]
	v_cvt_pk_bf16_f32 v84, v88, v89
	v_cvt_pk_bf16_f32 v85, v90, v91
	v_cvt_pk_bf16_f32 v86, v86, v87
	v_cvt_pk_bf16_f32 v87, v92, v93
	global_store_dwordx4 v[96:97], v[84:87], off offset:256 sc1 nt
	v_lshlrev_b32_e32 v88, 16, v137
	v_and_b32_e32 v89, 0xffff0000, v137
	v_lshlrev_b32_e32 v86, 16, v136
	v_and_b32_e32 v87, 0xffff0000, v136
	v_lshlrev_b64 v[84:85], 11, v[186:187]
	v_lshlrev_b32_e32 v90, 16, v138
	v_and_b32_e32 v91, 0xffff0000, v138
	v_lshlrev_b32_e32 v92, 16, v139
	v_and_b32_e32 v93, 0xffff0000, v139
	v_pk_mul_f32 v[80:81], v[80:81], v[86:87]
	v_pk_mul_f32 v[82:83], v[82:83], v[88:89]
	v_pk_mul_f32 v[86:87], v[78:79], v[92:93]
	v_pk_mul_f32 v[78:79], v[76:77], v[90:91]
	v_cvt_pk_bf16_f32 v76, v80, v81
	v_lshl_add_u64 v[80:81], s[6:7], 0, v[84:85]
	v_cvt_pk_bf16_f32 v77, v82, v83
	v_cvt_pk_bf16_f32 v78, v78, v79
	v_cvt_pk_bf16_f32 v79, v86, v87
	v_lshl_add_u64 v[80:81], v[80:81], 0, v[2:3]
	global_store_dwordx4 v[80:81], v[76:79], off sc1 nt
	v_lshlrev_b32_e32 v82, 16, v134
	v_and_b32_e32 v83, 0xffff0000, v134
	v_lshlrev_b32_e32 v76, 16, v132
	v_and_b32_e32 v77, 0xffff0000, v132
	v_lshlrev_b32_e32 v78, 16, v133
	v_and_b32_e32 v79, 0xffff0000, v133
	v_lshlrev_b32_e32 v84, 16, v135
	v_and_b32_e32 v85, 0xffff0000, v135
	v_pk_mul_f32 v[74:75], v[74:75], v[78:79]
	v_pk_mul_f32 v[72:73], v[72:73], v[76:77]
	v_pk_mul_f32 v[76:77], v[70:71], v[84:85]
	v_pk_mul_f32 v[70:71], v[68:69], v[82:83]
	v_add_u32_e32 v100, 0x80, v182
	v_cvt_pk_bf16_f32 v68, v72, v73
	v_cvt_pk_bf16_f32 v69, v74, v75
	v_cvt_pk_bf16_f32 v70, v70, v71
	v_cvt_pk_bf16_f32 v71, v76, v77
	v_ashrrev_i32_e32 v101, 31, v100
	global_store_dwordx4 v[80:81], v[68:71], off offset:256 sc1 nt
	v_add_u32_e32 v102, 0x90, v182
	v_ashrrev_i32_e32 v103, 31, v102
	v_lshlrev_b64 v[68:69], 12, v[100:101]
	v_lshl_add_u64 v[68:69], v[184:185], 0, v[68:69]
	v_lshlrev_b64 v[68:69], 12, v[102:103]
	v_lshl_add_u64 v[68:69], v[184:185], 0, v[68:69]
	v_add_u32_e32 v104, 0xa0, v182
	v_ashrrev_i32_e32 v105, 31, v104
	v_lshlrev_b64 v[68:69], 12, v[104:105]
	v_lshl_add_u64 v[68:69], v[184:185], 0, v[68:69]
	v_add_u32_e32 v106, 0xb0, v182
	v_ashrrev_i32_e32 v107, 31, v106
	v_lshlrev_b64 v[68:69], 12, v[106:107]
	v_lshl_add_u64 v[68:69], v[184:185], 0, v[68:69]
	s_nop 0
	v_lshlrev_b64 v[100:101], 11, v[100:101]
	s_waitcnt vmcnt(0)
	v_mov_b64_e32 v[72:73], v[218:219]
	v_mov_b64_e32 v[74:75], v[220:221]
	v_mov_b64_e32 v[76:77], v[222:223]
	v_mov_b64_e32 v[78:79], v[224:225]
	v_mov_b64_e32 v[80:81], v[226:227]
	v_mov_b64_e32 v[82:83], v[228:229]
	v_mov_b64_e32 v[84:85], v[230:231]
	v_mov_b64_e32 v[86:87], v[232:233]
	v_mov_b64_e32 v[88:89], v[234:235]
	v_mov_b64_e32 v[90:91], v[236:237]
	v_mov_b64_e32 v[92:93], v[238:239]
	v_mov_b64_e32 v[94:95], v[240:241]
	v_mov_b64_e32 v[96:97], v[242:243]
	v_mov_b64_e32 v[98:99], v[244:245]
	v_mov_b64_e32 v[68:69], v[246:247]
	v_mov_b64_e32 v[70:71], v[248:249]
	v_lshlrev_b32_e32 v108, 16, v72
	v_and_b32_e32 v109, 0xffff0000, v72
	v_lshlrev_b32_e32 v72, 16, v73
	v_and_b32_e32 v73, 0xffff0000, v73
	v_lshlrev_b32_e32 v110, 16, v74
	v_and_b32_e32 v111, 0xffff0000, v74
	v_lshlrev_b32_e32 v74, 16, v75
	v_and_b32_e32 v75, 0xffff0000, v75
	v_pk_mul_f32 v[64:65], v[64:65], v[108:109]
	v_pk_mul_f32 v[66:67], v[66:67], v[72:73]
	v_pk_mul_f32 v[72:73], v[62:63], v[74:75]
	v_pk_mul_f32 v[62:63], v[60:61], v[110:111]
	v_cvt_pk_bf16_f32 v60, v64, v65
	v_lshl_add_u64 v[64:65], s[6:7], 0, v[100:101]
	v_cvt_pk_bf16_f32 v61, v66, v67
	v_cvt_pk_bf16_f32 v62, v62, v63
	v_cvt_pk_bf16_f32 v63, v72, v73
	v_lshl_add_u64 v[64:65], v[64:65], 0, v[2:3]
	global_store_dwordx4 v[64:65], v[60:63], off sc1 nt
	v_lshlrev_b32_e32 v66, 16, v78
	v_and_b32_e32 v67, 0xffff0000, v78
	v_lshlrev_b32_e32 v60, 16, v76
	v_and_b32_e32 v61, 0xffff0000, v76
	v_lshlrev_b32_e32 v62, 16, v77
	v_and_b32_e32 v63, 0xffff0000, v77
	v_lshlrev_b32_e32 v72, 16, v79
	v_and_b32_e32 v73, 0xffff0000, v79
	v_pk_mul_f32 v[58:59], v[58:59], v[62:63]
	v_pk_mul_f32 v[56:57], v[56:57], v[60:61]
	v_pk_mul_f32 v[60:61], v[54:55], v[72:73]
	v_pk_mul_f32 v[54:55], v[52:53], v[66:67]
	v_cvt_pk_bf16_f32 v52, v56, v57
	v_cvt_pk_bf16_f32 v53, v58, v59
	v_cvt_pk_bf16_f32 v54, v54, v55
	v_cvt_pk_bf16_f32 v55, v60, v61
	global_store_dwordx4 v[64:65], v[52:55], off offset:256 sc1 nt
	v_lshlrev_b32_e32 v56, 16, v81
	v_and_b32_e32 v57, 0xffff0000, v81
	v_lshlrev_b32_e32 v54, 16, v80
	v_and_b32_e32 v55, 0xffff0000, v80
	v_lshlrev_b64 v[52:53], 11, v[102:103]
	v_lshlrev_b32_e32 v58, 16, v82
	v_and_b32_e32 v59, 0xffff0000, v82
	v_lshlrev_b32_e32 v60, 16, v83
	v_and_b32_e32 v61, 0xffff0000, v83
	v_pk_mul_f32 v[48:49], v[48:49], v[54:55]
	v_pk_mul_f32 v[50:51], v[50:51], v[56:57]
	v_pk_mul_f32 v[54:55], v[46:47], v[60:61]
	v_pk_mul_f32 v[46:47], v[44:45], v[58:59]
	v_cvt_pk_bf16_f32 v44, v48, v49
	v_lshl_add_u64 v[48:49], s[6:7], 0, v[52:53]
	v_cvt_pk_bf16_f32 v45, v50, v51
	v_cvt_pk_bf16_f32 v46, v46, v47
	v_cvt_pk_bf16_f32 v47, v54, v55
	v_lshl_add_u64 v[48:49], v[48:49], 0, v[2:3]
	global_store_dwordx4 v[48:49], v[44:47], off sc1 nt
	v_lshlrev_b32_e32 v50, 16, v86
	v_and_b32_e32 v51, 0xffff0000, v86
	v_lshlrev_b32_e32 v44, 16, v84
	v_and_b32_e32 v45, 0xffff0000, v84
	v_lshlrev_b32_e32 v46, 16, v85
	v_and_b32_e32 v47, 0xffff0000, v85
	v_lshlrev_b32_e32 v52, 16, v87
	v_and_b32_e32 v53, 0xffff0000, v87
	v_pk_mul_f32 v[42:43], v[42:43], v[46:47]
	v_pk_mul_f32 v[40:41], v[40:41], v[44:45]
	v_pk_mul_f32 v[44:45], v[38:39], v[52:53]
	v_pk_mul_f32 v[38:39], v[36:37], v[50:51]
	v_cvt_pk_bf16_f32 v36, v40, v41
	v_cvt_pk_bf16_f32 v37, v42, v43
	v_cvt_pk_bf16_f32 v38, v38, v39
	v_cvt_pk_bf16_f32 v39, v44, v45
	global_store_dwordx4 v[48:49], v[36:39], off offset:256 sc1 nt
	v_lshlrev_b32_e32 v40, 16, v89
	v_and_b32_e32 v41, 0xffff0000, v89
	v_lshlrev_b32_e32 v38, 16, v88
	v_and_b32_e32 v39, 0xffff0000, v88
	v_lshlrev_b64 v[36:37], 11, v[104:105]
	v_lshlrev_b32_e32 v42, 16, v90
	v_and_b32_e32 v43, 0xffff0000, v90
	v_lshlrev_b32_e32 v44, 16, v91
	v_and_b32_e32 v45, 0xffff0000, v91
	v_pk_mul_f32 v[32:33], v[32:33], v[38:39]
	v_pk_mul_f32 v[34:35], v[34:35], v[40:41]
	v_pk_mul_f32 v[38:39], v[30:31], v[44:45]
	v_pk_mul_f32 v[30:31], v[28:29], v[42:43]
	v_cvt_pk_bf16_f32 v28, v32, v33
	v_lshl_add_u64 v[32:33], s[6:7], 0, v[36:37]
	v_cvt_pk_bf16_f32 v29, v34, v35
	v_cvt_pk_bf16_f32 v30, v30, v31
	v_cvt_pk_bf16_f32 v31, v38, v39
	v_lshl_add_u64 v[32:33], v[32:33], 0, v[2:3]
	global_store_dwordx4 v[32:33], v[28:31], off sc1 nt
	v_lshlrev_b32_e32 v34, 16, v94
	v_and_b32_e32 v35, 0xffff0000, v94
	v_lshlrev_b32_e32 v28, 16, v92
	v_and_b32_e32 v29, 0xffff0000, v92
	v_lshlrev_b32_e32 v30, 16, v93
	v_and_b32_e32 v31, 0xffff0000, v93
	v_lshlrev_b32_e32 v36, 16, v95
	v_and_b32_e32 v37, 0xffff0000, v95
	v_pk_mul_f32 v[26:27], v[26:27], v[30:31]
	v_pk_mul_f32 v[24:25], v[24:25], v[28:29]
	v_pk_mul_f32 v[28:29], v[22:23], v[36:37]
	v_pk_mul_f32 v[22:23], v[20:21], v[34:35]
	v_cvt_pk_bf16_f32 v20, v24, v25
	v_cvt_pk_bf16_f32 v21, v26, v27
	v_cvt_pk_bf16_f32 v22, v22, v23
	v_cvt_pk_bf16_f32 v23, v28, v29
	global_store_dwordx4 v[32:33], v[20:23], off offset:256 sc1 nt
	v_lshlrev_b32_e32 v24, 16, v97
	v_and_b32_e32 v25, 0xffff0000, v97
	v_lshlrev_b32_e32 v22, 16, v96
	v_and_b32_e32 v23, 0xffff0000, v96
	v_lshlrev_b64 v[20:21], 11, v[106:107]
	v_lshlrev_b32_e32 v26, 16, v98
	v_and_b32_e32 v27, 0xffff0000, v98
	v_lshlrev_b32_e32 v28, 16, v99
	v_and_b32_e32 v29, 0xffff0000, v99
	v_pk_mul_f32 v[16:17], v[16:17], v[22:23]
	v_pk_mul_f32 v[18:19], v[18:19], v[24:25]
	v_pk_mul_f32 v[22:23], v[14:15], v[28:29]
	v_pk_mul_f32 v[14:15], v[12:13], v[26:27]
	v_cvt_pk_bf16_f32 v12, v16, v17
	v_lshl_add_u64 v[16:17], s[6:7], 0, v[20:21]
	v_cvt_pk_bf16_f32 v13, v18, v19
	v_cvt_pk_bf16_f32 v14, v14, v15
	v_cvt_pk_bf16_f32 v15, v22, v23
	v_lshl_add_u64 v[16:17], v[16:17], 0, v[2:3]
	global_store_dwordx4 v[16:17], v[12:15], off sc1 nt
	v_lshlrev_b32_e32 v2, 16, v68
	v_and_b32_e32 v3, 0xffff0000, v68
	v_lshlrev_b32_e32 v12, 16, v69
	v_and_b32_e32 v13, 0xffff0000, v69
	v_lshlrev_b32_e32 v14, 16, v70
	v_and_b32_e32 v15, 0xffff0000, v70
	v_lshlrev_b32_e32 v18, 16, v71
	v_and_b32_e32 v19, 0xffff0000, v71
	v_pk_mul_f32 v[10:11], v[10:11], v[12:13]
	v_pk_mul_f32 v[2:3], v[8:9], v[2:3]
	v_pk_mul_f32 v[6:7], v[6:7], v[18:19]
	v_pk_mul_f32 v[4:5], v[4:5], v[14:15]
	v_cvt_pk_bf16_f32 v2, v2, v3
	v_cvt_pk_bf16_f32 v3, v10, v11
	v_cvt_pk_bf16_f32 v4, v4, v5
	v_cvt_pk_bf16_f32 v5, v6, v7
	global_store_dwordx4 v[16:17], v[2:5], off offset:256 sc1 nt
	s_cbranch_vccnz .LBB0_118
	v_readlane_b32 s0, v252, 41
	v_readlane_b32 s1, v252, 42
	s_andn2_b64 vcc, exec, s[0:1]
	s_cbranch_vccnz .LBB0_117
	s_barrier
	s_branch .LBB0_117
